# kernel entry: all kernarg scalar loads issued in one round trip (were three serialized round trips)
# speedup vs baseline: 1.0038x; 1.0038x over previous
; #define LAS __attribute__((address_space(3)))
; __global__ void __launch_bounds__(NWAVES * 64, 2) fwd(Args args) {
;     extern __shared__ __attribute__((aligned(16))) unsigned char lds_raw[];
;     LAS unsigned char* lds = (LAS unsigned char*)lds_raw;
;     volatile LAS unsigned* MISC = (volatile LAS unsigned*)(lds + MISC_OFF);
;     const int tid = threadIdx.x, lane = tid & 63, wave = __builtin_amdgcn_readfirstlane(tid >> 6);
;     const int G = gridDim.x; const int bx = blockIdx.x; const int vcu = (G % 8 == 0) ? (bx % 8) * (G / 8) + bx / 8 : bx;
;     unsigned char* ws = args.ws;
;     gu32* ctl = (gu32*)(ws + WS_CTL);
;     const float* x = args.in[0]; const float* lbl = args.in[1]; const float* w_in = args.in[2];
;     const float* A_log = args.in[5]; const float* dt_bias = args.in[6];
;     const float* wba = args.in[8]; const float* wbb = args.in[9]; const float* wo = args.in[10]; const float* ln1g = args.in[11];
;     const float* ln1b = args.in[12]; const float* wup = args.in[13]; const float* wdn = args.in[14]; const float* ln2g = args.in[15]; const float* ln2b = args.in[16];
;     float* out = args.out;
;     bf16_t* WIN_T = (bf16_t*)(ws + WS_WIN); bf16_t* WING_T = (bf16_t*)(ws + WS_WING); bf16_t* WBAB_T = (bf16_t*)(ws + WS_WBAB); bf16_t* WO_T = (bf16_t*)(ws + WS_WO); bf16_t* WUP_T = (bf16_t*)(ws + WS_WUP); bf16_t* WDN_T = (bf16_t*)(ws + WS_WDN);
;     bf16_t* XB = (bf16_t*)(ws + WS_XB); bf16_t* HGR = (bf16_t*)(ws + WS_HGR); bf16_t* DNR = (bf16_t*)(ws + WS_DNR); bf16_t* HALO = (bf16_t*)(ws + WS_HALO);
;     bf16_t* GAB = (bf16_t*)args.out; bf16_t* OAB = (bf16_t*)(ws + WS_DNR) + 8192;     bf16_t* MRG = (bf16_t*)(ws + WS_MRG); bf16_t* H1B = (bf16_t*)(ws + WS_XB); bf16_t* HB = (bf16_t*)(ws + WS_HB);
;     float* GBT = (float*)(ws + WS_GBT); float* DEC = (float*)(ws + WS_DEC); bf16_t* OLH = (bf16_t*)(ws + WS_OLH); bf16_t* OLD = (bf16_t*)(ws + WS_OLD); bf16_t* BNB = (bf16_t*)(ws + WS_BNB);
;     for (int u = tid; u < (LDS_BYTES - LDSCTL_OFF) / 4; u += NWAVES * 64) ((LAS unsigned*)(lds + LDSCTL_OFF))[u] = 0u;
;     __syncthreads();
;     const int lo = args.ph_lo, hi = args.ph_hi;
;     XcdBarrier bar; bar.bar = (unsigned*)(ctl + CW_BAR) + args.li * XCD_BAR_WORDS; bar.x = 0; bar.st = MISC + 8;
;     if (hi - lo > 1) bar = xcd_barrier_post((unsigned*)(ctl + CW_BAR) + args.li * XCD_BAR_WORDS, MISC + 8);
_Z3fwd4Args:
	s_load_dword s34, s[0:1], 0xa8
	s_load_dwordx2 s[60:61], s[0:1], 0x90
	s_load_dwordx4 s[52:55], s[0:1], 0x80
	s_load_dwordx4 s[56:59], s[0:1], 0x98
	s_load_dwordx16 s[16:31], s[0:1], 0x0
	s_add_u32 s4, s0, 0xa8
	s_addc_u32 s5, s1, 0
	v_readfirstlane_b32 s66, v0
	v_writelane_b32 v240, s4, 0
	s_waitcnt lgkmcnt(0)
	s_and_b32 s3, s34, 7
	s_cmp_lg_u32 s3, 0
	s_mov_b32 s8, s2
	v_writelane_b32 v240, s5, 1
	s_cbranch_scc1 .LBB0_2
	s_ashr_i32 s4, s2, 31
	s_lshr_b32 s4, s4, 29
	s_add_i32 s4, s2, s4
	s_and_b32 s5, s4, -8
	s_ashr_i32 s3, s34, 3
	s_sub_i32 s5, s2, s5
	s_mul_i32 s3, s3, s5
	s_ashr_i32 s4, s4, 3
	s_add_i32 s8, s3, s4
.LBB0_2:
	v_lshl_add_u32 v184, v0, 2, 0
	v_mov_b32_e32 v2, 0
	v_add_u32_e32 v1, 0x22800, v184
	ds_write2st64_b32 v1, v2, v2 offset1:8
	ds_write2st64_b32 v1, v2, v2 offset0:16 offset1:24
	v_or_b32_e32 v1, 0x800, v0
	s_mov_b64 s[4:5], -1
	s_and_saveexec_b64 s[6:7], s[4:5]
	v_lshl_add_u32 v3, v1, 2, 0
	v_add_u32_e32 v3, 0x22800, v3
	ds_write_b32 v3, v2
	s_or_b64 exec, exec, s[6:7]
	s_and_saveexec_b64 s[6:7], s[4:5]
	s_add_i32 s3, 0, 0x22800
	v_lshl_add_u32 v1, v1, 2, s3
	v_mov_b32_e32 v2, 0
	ds_write_b32 v1, v2 offset:2048
	s_or_b64 exec, exec, s[6:7]
	v_or_b32_e32 v1, 0xc00, v0
	v_cmp_gt_u32_e64 s[4:5], 7, 6
	v_cmp_gt_u32_e64 s[10:11], 7, 5
	s_and_saveexec_b64 s[6:7], s[10:11]
	v_lshl_add_u32 v2, v1, 2, 0
	v_add_u32_e32 v2, 0x22800, v2
	v_mov_b32_e32 v3, 0
	ds_write_b32 v2, v3
	s_or_b64 exec, exec, s[6:7]
	s_and_saveexec_b64 s[6:7], s[4:5]
	s_add_i32 s3, 0, 0x22800
	v_lshl_add_u32 v1, v1, 2, s3
	v_mov_b32_e32 v2, 0
	ds_write_b32 v1, v2 offset:2048
	s_or_b64 exec, exec, s[6:7]
	s_waitcnt lgkmcnt(0)
	s_mul_i32 s4, s58, 0xd80
	s_ashr_i32 s5, s4, 31
	s_lshl_b64 s[4:5], s[4:5], 2
	s_add_u32 s3, s60, s4
	s_addc_u32 s4, s61, s5
	s_add_u32 s58, s3, 0x4000
	s_addc_u32 s59, s4, 0
	s_sub_i32 s3, s57, s56
	s_mov_b32 s90, 0
	s_cmp_lt_i32 s3, 2
	v_cmp_eq_u32_e32 vcc, 0, v0
	s_barrier
	s_cbranch_scc1 .LBB0_15
	s_getreg_b32 s3, hwreg(HW_REG_XCC_ID, 0, 4)
	s_and_b32 s90, s3, 15
	s_and_saveexec_b64 s[4:5], vcc
	s_cbranch_execz .LBB0_14
	s_mov_b64 s[6:7], exec
	v_mbcnt_lo_u32_b32 v1, s6, 0
	v_mbcnt_hi_u32_b32 v1, s7, v1
	v_cmp_eq_u32_e32 vcc, 0, v1
	s_and_b64 s[10:11], exec, vcc
	s_mov_b64 exec, s[10:11]
	s_cbranch_execz .LBB0_14
	s_lshl_b32 s3, s90, 8
	s_bcnt1_i32_b64 s6, s[6:7]
	v_mov_b32_e32 v1, s3
	v_mov_b32_e32 v2, s6
	global_atomic_add v1, v2, s[58:59] offset:1024

; __host__ __device__ __forceinline__ int tile_slot(int pn) { if (pn >= 16) return pn - 12; const int q = pn & 7; if (q >= 6) return (pn >> 3) * 2 + (q - 6); return (pn >> 3) * 6 + q; }
; #define LAS __attribute__((address_space(3)))
; __device__ __forceinline__ unsigned long long rt() { return __builtin_amdgcn_s_memrealtime(); }
; __global__ void __launch_bounds__(NWAVES * 64, 2) fwd(Args args) {
;     ...
;     if (IN(0)) {
;         const unsigned long long amp_t0_0 = (PROBE_AMP == 0) ? rt() : 0ull;
;         _Pragma("unroll 1") for (int rep_ = 0; rep_ < ((PROBE == 0) ? 2 : 1); ++rep_) {
;         const int gw = vcu * NWAVES + wave, NGW = G * NWAVES;
;         LAS float* scr = (LAS float*)(lds + RING_OFF + wave * 8704);
;         constexpr int I_IN = 16 * 192;
;         for (int it = gw; it < I_IN; it += NGW) { const int kb = it / 192, nb = it % 192, pn = nb >> 3, row = tile_slot(pn) * 256 + (nb & 7) * 32;
;             p0_transpose_item(w_in, PROJW, orig_col(32 * nb), 64 * kb, tile_is_late(pn) ? WING_T : WIN_T, 1024, row, 0, scr, lane); }
.LBB0_17:
	s_or_b64 exec, exec, s[6:7]
	s_add_u32 s84, s60, 0x600000
	s_addc_u32 s5, s61, 0
	s_add_u32 s64, s60, 0xc00000
	s_addc_u32 s65, s61, 0
	s_lshr_b32 s48, s66, 6
	s_cmp_lt_i32 s56, 1
	s_cselect_b64 s[6:7], -1, 0
	s_cmp_gt_i32 s57, 0
	s_cselect_b64 s[10:11], -1, 0
	s_and_b64 s[6:7], s[6:7], s[10:11]
	s_andn2_b64 vcc, exec, s[6:7]
	v_and_b32_e32 v234, 63, v0
	v_writelane_b32 v240, s48, 2
	s_cbranch_vccnz .LBB0_123
	s_lshl_b32 s3, s8, 3
	s_add_i32 s40, s3, s48
	s_lshl_b32 s42, s34, 3
	v_lshrrev_b32_e32 v8, 3, v234
	s_cmpk_gt_i32 s40, 0xbff
	v_lshlrev_b32_e32 v9, 3, v0
	v_mov_b32_e32 v3, 0
	v_lshlrev_b32_e32 v34, 2, v8
	s_cbranch_scc1 .LBB0_43
	s_mul_i32 s3, s48, 0x2200
	v_lshlrev_b32_e32 v1, 4, v0
	s_add_i32 s3, s3, 0
	v_and_b32_e32 v2, 0x70, v1
	s_waitcnt lgkmcnt(0)
	v_lshl_add_u64 v[4:5], s[20:21], 0, v[2:3]
	v_add_u32_e32 v15, s3, v2
	v_mul_u32_u24_e32 v16, 0x84, v8
	v_and_b32_e32 v2, 56, v9
	v_mul_u32_u24_e32 v14, 0x84, v2
	v_add_u32_e32 v15, v15, v16
	v_or_b32_e32 v1, 8, v8
	v_or_b32_e32 v6, 16, v8
	v_or_b32_e32 v7, 24, v8
	v_or_b32_e32 v10, 32, v8
	v_or_b32_e32 v11, 40, v8
	v_or_b32_e32 v12, 48, v8
	v_or_b32_e32 v13, 56, v8
	v_add3_u32 v14, s3, v14, v34
	s_lshl_b32 s3, s40, 5
	s_lshl_b32 s4, s42, 5
	s_lshl_b32 s12, s40, 8
	s_lshl_b32 s13, s42, 8
	s_movk_i32 s14, 0x6020
	v_add_u32_e32 v16, 0x420, v15
	v_add_u32_e32 v17, 0x428, v15
	v_add_u32_e32 v18, 0x840, v15
	v_add_u32_e32 v19, 0x848, v15
	v_add_u32_e32 v20, 0xc60, v15
	v_add_u32_e32 v21, 0xc68, v15
	v_add_u32_e32 v22, 0x1080, v15
	v_add_u32_e32 v23, 0x1088, v15
	v_add_u32_e32 v24, 0x14a0, v15
	v_add_u32_e32 v25, 0x14a8, v15
	v_add_u32_e32 v26, 0x18c0, v15
	v_add_u32_e32 v27, 0x18c8, v15
	v_add_u32_e32 v28, 0x1ce0, v15
	v_add_u32_e32 v29, 0x1ce8, v15
	v_lshlrev_b32_e32 v2, 1, v2
	s_mov_b32 s15, s40
	s_branch .LBB0_21
